# as v10 plus nt on the read-once 8-bit gate loads of the branch-merge GEMM
# speedup vs baseline: 1.0048x; 1.0048x over previous
.LBB0_1283:
	s_add_i32 s14, s54, s58
	s_cmp_lg_u32 s58, 0
	s_cselect_b64 s[60:61], -1, 0
	s_and_b32 s59, s14, 0xffffffef
	s_cmp_eq_u32 s59, 32
	s_cselect_b64 vcc, -1, 0
	s_and_b64 s[60:61], s[60:61], vcc
	s_andn2_b64 vcc, exec, s[60:61]
	s_cbranch_vccnz .LBB0_1285
	s_cmp_eq_u32 s14, 32
	s_cselect_b32 s14, 0, 0x1000
	v_lshl_add_u64 v[4:5], v[174:175], 0, s[14:15]
	v_lshl_add_u64 v[176:177], v[4:5], 0, v[158:159]
	v_add_co_u32_e32 v178, vcc, 0x1000, v176
	global_load_dwordx2 v[210:211], v[176:177], off nt
	s_nop 0
	v_addc_co_u32_e32 v179, vcc, 0, v177, vcc
	global_load_dwordx2 v[212:213], v[178:179], off nt
	global_load_dwordx2 v[200:201], v[176:177], off offset:128 nt
	global_load_dwordx2 v[202:203], v[178:179], off offset:128 nt
	v_lshl_add_u64 v[176:177], v[4:5], 0, v[160:161]
	v_add_co_u32_e32 v178, vcc, 0x1000, v176
	global_load_dwordx2 v[196:197], v[176:177], off nt
	s_nop 0
	v_addc_co_u32_e32 v179, vcc, 0, v177, vcc
	global_load_dwordx2 v[198:199], v[178:179], off nt
	global_load_dwordx2 v[190:191], v[176:177], off offset:128 nt
	global_load_dwordx2 v[194:195], v[178:179], off offset:128 nt
	v_lshl_add_u64 v[176:177], v[4:5], 0, v[162:163]
	v_add_co_u32_e32 v178, vcc, 0x1000, v176
	global_load_dwordx2 v[188:189], v[176:177], off nt
	s_nop 0
	v_addc_co_u32_e32 v179, vcc, 0, v177, vcc
	global_load_dwordx2 v[192:193], v[178:179], off nt
	global_load_dwordx2 v[180:181], v[176:177], off offset:128 nt
	global_load_dwordx2 v[186:187], v[178:179], off offset:128 nt
	v_lshl_add_u64 v[176:177], v[4:5], 0, v[164:165]
	v_add_co_u32_e32 v184, vcc, 0x1000, v176
	global_load_dwordx2 v[178:179], v[176:177], off nt
	s_nop 0
	v_addc_co_u32_e32 v185, vcc, 0, v177, vcc
	global_load_dwordx2 v[182:183], v[184:185], off nt
	s_nop 0
	global_load_dwordx2 v[176:177], v[176:177], off offset:128 nt
	s_nop 0
	global_load_dwordx2 v[184:185], v[184:185], off offset:128 nt
	s_waitcnt vmcnt(0)
	v_cvt_f32_ubyte1_e32 v223, v210
	v_cvt_f32_ubyte0_e32 v3, v212
	v_cvt_f32_ubyte1_e32 v153, v212
	v_cvt_f32_ubyte2_e32 v155, v212
	v_cvt_f32_ubyte3_e32 v157, v212
	v_cvt_f32_ubyte0_e32 v209, v213
	v_cvt_f32_ubyte1_e32 v217, v213
	v_cvt_f32_ubyte2_e32 v218, v213
	v_cvt_f32_ubyte3_e32 v219, v213
	v_rcp_iflag_f32_e32 v212, v3
	v_rcp_iflag_f32_e32 v213, v153
	v_rcp_iflag_f32_e32 v214, v155
	v_rcp_iflag_f32_e32 v215, v157
	v_rcp_iflag_f32_e32 v218, v218
	v_rcp_iflag_f32_e32 v219, v219
	v_rcp_iflag_f32_e32 v216, v209
	v_rcp_iflag_f32_e32 v217, v217
	v_cvt_f32_ubyte0_e32 v222, v210
	v_cvt_f32_ubyte3_e32 v221, v210
	v_cvt_f32_ubyte2_e32 v220, v210
	v_pk_mul_f32 v[212:213], v[212:213], v[222:223]
	v_pk_mul_f32 v[214:215], v[214:215], v[220:221]
	v_pk_mul_f32 v[106:107], v[106:107], v[212:213]
	v_cvt_f32_ubyte3_e32 v213, v211
	v_cvt_f32_ubyte2_e32 v212, v211
	v_pk_mul_f32 v[108:109], v[108:109], v[214:215]
	v_cvt_f32_ubyte1_e32 v215, v211
	v_cvt_f32_ubyte0_e32 v214, v211
	v_pk_mul_f32 v[212:213], v[218:219], v[212:213]
	v_cvt_f32_ubyte0_e32 v3, v202
	v_cvt_f32_ubyte1_e32 v153, v202
	v_pk_mul_f32 v[210:211], v[216:217], v[214:215]
	v_pk_mul_f32 v[116:117], v[116:117], v[212:213]
	v_cvt_f32_ubyte2_e32 v155, v202
	v_cvt_f32_ubyte3_e32 v157, v202
	v_cvt_f32_ubyte0_e32 v209, v203
	v_cvt_f32_ubyte1_e32 v213, v203
	v_cvt_f32_ubyte2_e32 v214, v203
	v_cvt_f32_ubyte3_e32 v215, v203
	v_rcp_iflag_f32_e32 v202, v3
	v_rcp_iflag_f32_e32 v203, v153
	v_pk_mul_f32 v[114:115], v[114:115], v[210:211]
	v_rcp_iflag_f32_e32 v210, v155
	v_rcp_iflag_f32_e32 v211, v157
	v_rcp_iflag_f32_e32 v214, v214
	v_rcp_iflag_f32_e32 v215, v215
	v_rcp_iflag_f32_e32 v212, v209
	v_rcp_iflag_f32_e32 v213, v213
	v_cvt_f32_ubyte1_e32 v219, v200
	v_cvt_f32_ubyte0_e32 v218, v200
	v_cvt_f32_ubyte3_e32 v217, v200
	v_cvt_f32_ubyte2_e32 v216, v200
	v_pk_mul_f32 v[202:203], v[202:203], v[218:219]
	v_pk_mul_f32 v[210:211], v[210:211], v[216:217]
	v_pk_mul_f32 v[126:127], v[126:127], v[202:203]
	v_cvt_f32_ubyte3_e32 v203, v201
	v_cvt_f32_ubyte2_e32 v202, v201
	v_pk_mul_f32 v[128:129], v[128:129], v[210:211]
	v_cvt_f32_ubyte1_e32 v211, v201
	v_cvt_f32_ubyte0_e32 v210, v201
	v_pk_mul_f32 v[202:203], v[214:215], v[202:203]
	v_cvt_f32_ubyte0_e32 v3, v198
	v_cvt_f32_ubyte1_e32 v153, v198
	v_pk_mul_f32 v[200:201], v[212:213], v[210:211]
	v_pk_mul_f32 v[132:133], v[132:133], v[202:203]
	v_cvt_f32_ubyte2_e32 v155, v198
	v_cvt_f32_ubyte3_e32 v157, v198
	v_cvt_f32_ubyte0_e32 v202, v199
	v_cvt_f32_ubyte1_e32 v203, v199
	v_cvt_f32_ubyte2_e32 v209, v199
	v_cvt_f32_ubyte3_e32 v211, v199
	v_rcp_iflag_f32_e32 v198, v3
	v_rcp_iflag_f32_e32 v199, v153
	v_pk_mul_f32 v[130:131], v[130:131], v[200:201]
	v_rcp_iflag_f32_e32 v200, v155
	v_rcp_iflag_f32_e32 v201, v157
	v_rcp_iflag_f32_e32 v210, v209
	v_rcp_iflag_f32_e32 v211, v211
	v_rcp_iflag_f32_e32 v202, v202
	v_rcp_iflag_f32_e32 v203, v203
	v_cvt_f32_ubyte1_e32 v215, v196
	v_cvt_f32_ubyte0_e32 v214, v196
	v_cvt_f32_ubyte3_e32 v213, v196
	v_cvt_f32_ubyte2_e32 v212, v196
	v_pk_mul_f32 v[198:199], v[198:199], v[214:215]
	v_pk_mul_f32 v[200:201], v[200:201], v[212:213]
	v_pk_mul_f32 v[102:103], v[102:103], v[198:199]
	v_cvt_f32_ubyte3_e32 v199, v197
	v_cvt_f32_ubyte2_e32 v198, v197
	v_pk_mul_f32 v[104:105], v[104:105], v[200:201]
	v_cvt_f32_ubyte1_e32 v201, v197
	v_cvt_f32_ubyte0_e32 v200, v197
	v_pk_mul_f32 v[198:199], v[210:211], v[198:199]
	v_cvt_f32_ubyte0_e32 v3, v194
	v_cvt_f32_ubyte1_e32 v153, v194
	v_pk_mul_f32 v[196:197], v[202:203], v[200:201]
	v_pk_mul_f32 v[112:113], v[112:113], v[198:199]
	v_cvt_f32_ubyte2_e32 v155, v194
	v_cvt_f32_ubyte3_e32 v157, v194
	v_cvt_f32_ubyte0_e32 v198, v195
	v_cvt_f32_ubyte1_e32 v199, v195
	v_cvt_f32_ubyte2_e32 v200, v195
	v_cvt_f32_ubyte3_e32 v201, v195
	v_rcp_iflag_f32_e32 v194, v3
	v_rcp_iflag_f32_e32 v195, v153
	v_pk_mul_f32 v[110:111], v[110:111], v[196:197]
	v_rcp_iflag_f32_e32 v196, v155
	v_rcp_iflag_f32_e32 v197, v157
	v_rcp_iflag_f32_e32 v200, v200
	v_rcp_iflag_f32_e32 v201, v201
	v_rcp_iflag_f32_e32 v198, v198
	v_rcp_iflag_f32_e32 v199, v199
	v_cvt_f32_ubyte1_e32 v211, v190
	v_cvt_f32_ubyte0_e32 v210, v190
	v_cvt_f32_ubyte3_e32 v203, v190
	v_cvt_f32_ubyte2_e32 v202, v190
	v_pk_mul_f32 v[194:195], v[194:195], v[210:211]
	v_pk_mul_f32 v[196:197], v[196:197], v[202:203]
	v_pk_mul_f32 v[122:123], v[122:123], v[194:195]
	v_cvt_f32_ubyte3_e32 v195, v191
	v_cvt_f32_ubyte2_e32 v194, v191
	v_pk_mul_f32 v[124:125], v[124:125], v[196:197]
	v_cvt_f32_ubyte1_e32 v197, v191
	v_cvt_f32_ubyte0_e32 v196, v191
	v_pk_mul_f32 v[194:195], v[200:201], v[194:195]
	v_cvt_f32_ubyte2_e32 v155, v192
	v_cvt_f32_ubyte3_e32 v157, v192
	v_pk_mul_f32 v[190:191], v[198:199], v[196:197]
	v_pk_mul_f32 v[120:121], v[120:121], v[194:195]
	v_cvt_f32_ubyte0_e32 v3, v192
	v_cvt_f32_ubyte1_e32 v153, v192
	v_cvt_f32_ubyte0_e32 v194, v193
	v_cvt_f32_ubyte1_e32 v195, v193
	v_cvt_f32_ubyte2_e32 v196, v193
	v_cvt_f32_ubyte3_e32 v197, v193
	v_rcp_iflag_f32_e32 v192, v155
	v_rcp_iflag_f32_e32 v193, v157
	v_pk_mul_f32 v[118:119], v[118:119], v[190:191]
	v_rcp_iflag_f32_e32 v190, v3
	v_rcp_iflag_f32_e32 v191, v153
	v_rcp_iflag_f32_e32 v194, v194
	v_rcp_iflag_f32_e32 v195, v195
	v_rcp_iflag_f32_e32 v196, v196
	v_rcp_iflag_f32_e32 v197, v197
	v_cvt_f32_ubyte3_e32 v199, v188
	v_cvt_f32_ubyte2_e32 v198, v188
	v_cvt_f32_ubyte1_e32 v201, v188
	v_cvt_f32_ubyte0_e32 v200, v188
	v_pk_mul_f32 v[192:193], v[192:193], v[198:199]
	v_pk_mul_f32 v[190:191], v[190:191], v[200:201]
	v_pk_mul_f32 v[92:93], v[92:93], v[192:193]
	v_cvt_f32_ubyte1_e32 v193, v189
	v_cvt_f32_ubyte0_e32 v192, v189
	v_pk_mul_f32 v[90:91], v[90:91], v[190:191]
	v_cvt_f32_ubyte3_e32 v191, v189
	v_cvt_f32_ubyte2_e32 v190, v189
	v_pk_mul_f32 v[188:189], v[194:195], v[192:193]
	v_cvt_f32_ubyte2_e32 v155, v186
	v_cvt_f32_ubyte3_e32 v157, v186
	v_pk_mul_f32 v[190:191], v[196:197], v[190:191]
	v_pk_mul_f32 v[86:87], v[86:87], v[188:189]
	v_cvt_f32_ubyte0_e32 v3, v186
	v_cvt_f32_ubyte1_e32 v153, v186
	v_rcp_iflag_f32_e32 v188, v155
	v_rcp_iflag_f32_e32 v189, v157
	v_pk_mul_f32 v[88:89], v[88:89], v[190:191]
	v_cvt_f32_ubyte0_e32 v190, v187
	v_cvt_f32_ubyte1_e32 v191, v187
	v_cvt_f32_ubyte2_e32 v192, v187
	v_cvt_f32_ubyte3_e32 v193, v187
	v_rcp_iflag_f32_e32 v186, v3
	v_rcp_iflag_f32_e32 v187, v153
	v_rcp_iflag_f32_e32 v190, v190
	v_rcp_iflag_f32_e32 v191, v191
	v_rcp_iflag_f32_e32 v192, v192
	v_rcp_iflag_f32_e32 v193, v193
	v_cvt_f32_ubyte3_e32 v195, v180
	v_cvt_f32_ubyte2_e32 v194, v180
	v_cvt_f32_ubyte1_e32 v197, v180
	v_cvt_f32_ubyte0_e32 v196, v180
	v_pk_mul_f32 v[188:189], v[188:189], v[194:195]
	v_pk_mul_f32 v[186:187], v[186:187], v[196:197]
	v_pk_mul_f32 v[100:101], v[100:101], v[188:189]
	v_cvt_f32_ubyte1_e32 v189, v181
	v_cvt_f32_ubyte0_e32 v188, v181
	v_pk_mul_f32 v[98:99], v[98:99], v[186:187]
	v_cvt_f32_ubyte3_e32 v187, v181
	v_cvt_f32_ubyte2_e32 v186, v181
	v_pk_mul_f32 v[180:181], v[190:191], v[188:189]
	v_cvt_f32_ubyte0_e32 v3, v182
	v_cvt_f32_ubyte1_e32 v153, v182
	v_pk_mul_f32 v[186:187], v[192:193], v[186:187]
	v_pk_mul_f32 v[94:95], v[94:95], v[180:181]
	v_cvt_f32_ubyte2_e32 v155, v182
	v_cvt_f32_ubyte3_e32 v157, v182
	v_rcp_iflag_f32_e32 v180, v3
	v_rcp_iflag_f32_e32 v181, v153
	v_pk_mul_f32 v[96:97], v[96:97], v[186:187]
	v_cvt_f32_ubyte0_e32 v186, v183
	v_cvt_f32_ubyte1_e32 v187, v183
	v_cvt_f32_ubyte2_e32 v188, v183
	v_cvt_f32_ubyte3_e32 v189, v183
	v_rcp_iflag_f32_e32 v182, v155
	v_rcp_iflag_f32_e32 v183, v157
	v_rcp_iflag_f32_e32 v188, v188
	v_rcp_iflag_f32_e32 v189, v189
	v_rcp_iflag_f32_e32 v186, v186
	v_rcp_iflag_f32_e32 v187, v187
	v_cvt_f32_ubyte1_e32 v193, v178
	v_cvt_f32_ubyte0_e32 v192, v178
	v_cvt_f32_ubyte3_e32 v191, v178
	v_cvt_f32_ubyte2_e32 v190, v178
	v_pk_mul_f32 v[180:181], v[180:181], v[192:193]
	v_pk_mul_f32 v[182:183], v[182:183], v[190:191]
	v_pk_mul_f32 v[74:75], v[74:75], v[180:181]
	v_cvt_f32_ubyte3_e32 v181, v179
	v_cvt_f32_ubyte2_e32 v180, v179
	v_pk_mul_f32 v[76:77], v[76:77], v[182:183]
	v_cvt_f32_ubyte1_e32 v183, v179
	v_cvt_f32_ubyte0_e32 v182, v179
	v_pk_mul_f32 v[180:181], v[188:189], v[180:181]
	v_cvt_f32_ubyte2_e32 v155, v184
	v_cvt_f32_ubyte3_e32 v157, v184
	v_pk_mul_f32 v[178:179], v[186:187], v[182:183]
	v_pk_mul_f32 v[72:73], v[72:73], v[180:181]
	v_cvt_f32_ubyte0_e32 v3, v184
	v_cvt_f32_ubyte1_e32 v153, v184
	v_rcp_iflag_f32_e32 v180, v155
	v_rcp_iflag_f32_e32 v181, v157
	v_pk_mul_f32 v[70:71], v[70:71], v[178:179]
	v_cvt_f32_ubyte0_e32 v182, v185
	v_cvt_f32_ubyte1_e32 v183, v185
	v_rcp_iflag_f32_e32 v178, v3
	v_rcp_iflag_f32_e32 v179, v153
	v_cvt_f32_ubyte2_e32 v184, v185
	v_cvt_f32_ubyte3_e32 v185, v185
	v_rcp_iflag_f32_e32 v182, v182
	v_rcp_iflag_f32_e32 v183, v183
	v_rcp_iflag_f32_e32 v184, v184
	v_rcp_iflag_f32_e32 v185, v185
	v_cvt_f32_ubyte3_e32 v187, v176
	v_cvt_f32_ubyte2_e32 v186, v176
	v_cvt_f32_ubyte1_e32 v189, v176
	v_cvt_f32_ubyte0_e32 v188, v176
	v_pk_mul_f32 v[180:181], v[180:181], v[186:187]
	v_pk_mul_f32 v[178:179], v[178:179], v[188:189]
	v_pk_mul_f32 v[84:85], v[84:85], v[180:181]
	v_cvt_f32_ubyte1_e32 v181, v177
	v_cvt_f32_ubyte0_e32 v180, v177
	v_pk_mul_f32 v[82:83], v[82:83], v[178:179]
	v_cvt_f32_ubyte3_e32 v179, v177
	v_cvt_f32_ubyte2_e32 v178, v177
	v_pk_mul_f32 v[176:177], v[182:183], v[180:181]
	v_pk_mul_f32 v[178:179], v[184:185], v[178:179]
	v_pk_mul_f32 v[78:79], v[78:79], v[176:177]
	v_lshl_add_u64 v[176:177], v[4:5], 0, v[166:167]
	v_pk_mul_f32 v[80:81], v[80:81], v[178:179]
	v_add_co_u32_e32 v178, vcc, s89, v176
	global_load_dwordx2 v[194:195], v[176:177], off nt
	s_nop 0
	v_addc_co_u32_e32 v179, vcc, 0, v177, vcc
	global_load_dwordx2 v[196:197], v[178:179], off nt
	global_load_dwordx2 v[188:189], v[176:177], off offset:128 nt
	global_load_dwordx2 v[198:199], v[178:179], off offset:128 nt
	v_lshl_add_u64 v[176:177], v[4:5], 0, v[168:169]
	v_add_co_u32_e32 v178, vcc, s89, v176
	global_load_dwordx2 v[200:201], v[176:177], off nt
	s_nop 0
	v_addc_co_u32_e32 v179, vcc, 0, v177, vcc
	global_load_dwordx2 v[202:203], v[178:179], off nt
	global_load_dwordx2 v[192:193], v[176:177], off offset:128 nt
	global_load_dwordx2 v[210:211], v[178:179], off offset:128 nt
	v_lshl_add_u64 v[176:177], v[4:5], 0, v[170:171]
	v_add_co_u32_e32 v178, vcc, s89, v176
	global_load_dwordx2 v[186:187], v[176:177], off nt
	s_nop 0
	v_addc_co_u32_e32 v179, vcc, 0, v177, vcc
	global_load_dwordx2 v[190:191], v[178:179], off nt
	global_load_dwordx2 v[182:183], v[176:177], off offset:128 nt
	global_load_dwordx2 v[184:185], v[178:179], off offset:128 nt
	v_lshl_add_u64 v[4:5], v[4:5], 0, v[172:173]
	v_add_co_u32_e32 v176, vcc, s89, v4
	global_load_dwordx2 v[178:179], v[4:5], off nt
	s_nop 0
	v_addc_co_u32_e32 v177, vcc, 0, v5, vcc
	global_load_dwordx2 v[180:181], v[176:177], off nt
	s_nop 0
	global_load_dwordx2 v[4:5], v[4:5], off offset:128 nt
	s_nop 0
	global_load_dwordx2 v[176:177], v[176:177], off offset:128 nt
	s_waitcnt vmcnt(15)
	v_cvt_f32_ubyte3_e32 v219, v194
	s_waitcnt vmcnt(14)
	v_cvt_f32_ubyte0_e32 v3, v196
	v_cvt_f32_ubyte1_e32 v153, v196
	v_cvt_f32_ubyte2_e32 v155, v196
	v_cvt_f32_ubyte3_e32 v157, v196
	v_cvt_f32_ubyte0_e32 v209, v197
	v_cvt_f32_ubyte1_e32 v215, v197
	v_cvt_f32_ubyte2_e32 v216, v197
	v_cvt_f32_ubyte3_e32 v217, v197
	v_rcp_iflag_f32_e32 v196, v3
	v_rcp_iflag_f32_e32 v197, v153
	v_rcp_iflag_f32_e32 v212, v155
	v_rcp_iflag_f32_e32 v213, v157
	v_rcp_iflag_f32_e32 v214, v209
	v_rcp_iflag_f32_e32 v215, v215
	v_rcp_iflag_f32_e32 v216, v216
	v_rcp_iflag_f32_e32 v217, v217
	v_cvt_f32_ubyte2_e32 v218, v194
	v_cvt_f32_ubyte1_e32 v221, v194
	v_cvt_f32_ubyte0_e32 v220, v194
	v_pk_mul_f32 v[196:197], v[196:197], v[220:221]
	v_pk_mul_f32 v[212:213], v[212:213], v[218:219]
	v_pk_mul_f32 v[66:67], v[66:67], v[196:197]
	v_pk_mul_f32 v[68:69], v[68:69], v[212:213]
	v_cvt_f32_ubyte3_e32 v197, v195
	v_cvt_f32_ubyte2_e32 v196, v195
	v_cvt_f32_ubyte1_e32 v213, v195
	v_cvt_f32_ubyte0_e32 v212, v195
	v_pk_mul_f32 v[194:195], v[214:215], v[212:213]
	v_pk_mul_f32 v[196:197], v[216:217], v[196:197]
	s_waitcnt vmcnt(12)
	v_cvt_f32_ubyte0_e32 v3, v198
	v_cvt_f32_ubyte1_e32 v153, v198
	v_cvt_f32_ubyte2_e32 v155, v198
	v_cvt_f32_ubyte3_e32 v157, v198
	v_pk_mul_f32 v[60:61], v[60:61], v[196:197]
	v_pk_mul_f32 v[58:59], v[58:59], v[194:195]
	v_rcp_iflag_f32_e32 v194, v3
	v_rcp_iflag_f32_e32 v195, v153
	v_rcp_iflag_f32_e32 v196, v155
	v_rcp_iflag_f32_e32 v197, v157
	v_cvt_f32_ubyte0_e32 v198, v199
	v_cvt_f32_ubyte1_e32 v209, v199
	v_cvt_f32_ubyte2_e32 v212, v199
	v_cvt_f32_ubyte3_e32 v213, v199
	v_rcp_iflag_f32_e32 v198, v198
	v_rcp_iflag_f32_e32 v199, v209
	v_rcp_iflag_f32_e32 v212, v212
	v_rcp_iflag_f32_e32 v213, v213
	v_cvt_f32_ubyte3_e32 v215, v188
	v_cvt_f32_ubyte2_e32 v214, v188
	v_cvt_f32_ubyte1_e32 v217, v188
	v_cvt_f32_ubyte0_e32 v216, v188
	v_pk_mul_f32 v[194:195], v[194:195], v[216:217]
	v_pk_mul_f32 v[196:197], v[196:197], v[214:215]
	v_pk_mul_f32 v[62:63], v[62:63], v[194:195]
	v_pk_mul_f32 v[64:65], v[64:65], v[196:197]
	v_cvt_f32_ubyte3_e32 v195, v189
	v_cvt_f32_ubyte2_e32 v194, v189
	v_cvt_f32_ubyte1_e32 v197, v189
	v_cvt_f32_ubyte0_e32 v196, v189
	v_pk_mul_f32 v[188:189], v[198:199], v[196:197]
	v_pk_mul_f32 v[194:195], v[212:213], v[194:195]
	s_waitcnt vmcnt(10)
	v_cvt_f32_ubyte0_e32 v3, v202
	v_cvt_f32_ubyte1_e32 v153, v202
	v_cvt_f32_ubyte2_e32 v155, v202
	v_cvt_f32_ubyte3_e32 v157, v202
	v_pk_mul_f32 v[56:57], v[56:57], v[194:195]
	v_pk_mul_f32 v[54:55], v[54:55], v[188:189]
	v_rcp_iflag_f32_e32 v188, v3
	v_rcp_iflag_f32_e32 v189, v153
	v_rcp_iflag_f32_e32 v194, v155
	v_rcp_iflag_f32_e32 v195, v157
	v_cvt_f32_ubyte0_e32 v196, v203
	v_cvt_f32_ubyte1_e32 v197, v203
	v_cvt_f32_ubyte2_e32 v198, v203
	v_cvt_f32_ubyte3_e32 v199, v203
	v_rcp_iflag_f32_e32 v196, v196
	v_rcp_iflag_f32_e32 v197, v197
	v_rcp_iflag_f32_e32 v198, v198
	v_rcp_iflag_f32_e32 v199, v199
	v_cvt_f32_ubyte3_e32 v203, v200
	v_cvt_f32_ubyte2_e32 v202, v200
	v_cvt_f32_ubyte1_e32 v213, v200
	v_cvt_f32_ubyte0_e32 v212, v200
	v_pk_mul_f32 v[188:189], v[188:189], v[212:213]
	v_pk_mul_f32 v[194:195], v[194:195], v[202:203]
	v_pk_mul_f32 v[50:51], v[50:51], v[188:189]
	v_pk_mul_f32 v[52:53], v[52:53], v[194:195]
	v_cvt_f32_ubyte3_e32 v189, v201
	v_cvt_f32_ubyte2_e32 v188, v201
	v_cvt_f32_ubyte1_e32 v195, v201
	v_cvt_f32_ubyte0_e32 v194, v201
	v_pk_mul_f32 v[194:195], v[196:197], v[194:195]
	v_pk_mul_f32 v[188:189], v[198:199], v[188:189]
	s_waitcnt vmcnt(8)
	v_cvt_f32_ubyte0_e32 v3, v210
	v_cvt_f32_ubyte1_e32 v153, v210
	v_cvt_f32_ubyte2_e32 v155, v210
	v_cvt_f32_ubyte3_e32 v157, v210
	v_pk_mul_f32 v[44:45], v[44:45], v[188:189]
	v_pk_mul_f32 v[42:43], v[42:43], v[194:195]
	v_rcp_iflag_f32_e32 v188, v3
	v_rcp_iflag_f32_e32 v189, v153
	v_rcp_iflag_f32_e32 v194, v155
	v_rcp_iflag_f32_e32 v195, v157
	v_cvt_f32_ubyte0_e32 v196, v211
	v_cvt_f32_ubyte1_e32 v197, v211
	v_cvt_f32_ubyte2_e32 v198, v211
	v_cvt_f32_ubyte3_e32 v199, v211
	v_rcp_iflag_f32_e32 v196, v196
	v_rcp_iflag_f32_e32 v197, v197
	v_rcp_iflag_f32_e32 v198, v198
	v_rcp_iflag_f32_e32 v199, v199
	v_cvt_f32_ubyte3_e32 v201, v192
	v_cvt_f32_ubyte2_e32 v200, v192
	v_cvt_f32_ubyte1_e32 v203, v192
	v_cvt_f32_ubyte0_e32 v202, v192
	v_pk_mul_f32 v[188:189], v[188:189], v[202:203]
	v_pk_mul_f32 v[194:195], v[194:195], v[200:201]
	v_pk_mul_f32 v[46:47], v[46:47], v[188:189]
	v_pk_mul_f32 v[48:49], v[48:49], v[194:195]
	v_cvt_f32_ubyte3_e32 v189, v193
	v_cvt_f32_ubyte2_e32 v188, v193
	v_cvt_f32_ubyte1_e32 v195, v193
	v_cvt_f32_ubyte0_e32 v194, v193
	v_pk_mul_f32 v[192:193], v[196:197], v[194:195]
	v_pk_mul_f32 v[188:189], v[198:199], v[188:189]
	s_waitcnt vmcnt(6)
	v_cvt_f32_ubyte0_e32 v3, v190
	v_cvt_f32_ubyte1_e32 v153, v190
	v_cvt_f32_ubyte2_e32 v155, v190
	v_cvt_f32_ubyte3_e32 v157, v190
	v_pk_mul_f32 v[40:41], v[40:41], v[188:189]
	v_pk_mul_f32 v[38:39], v[38:39], v[192:193]
	v_cvt_f32_ubyte0_e32 v192, v191
	v_cvt_f32_ubyte1_e32 v193, v191
	v_cvt_f32_ubyte2_e32 v194, v191
	v_cvt_f32_ubyte3_e32 v195, v191
	v_rcp_iflag_f32_e32 v188, v3
	v_rcp_iflag_f32_e32 v189, v153
	v_rcp_iflag_f32_e32 v190, v155
	v_rcp_iflag_f32_e32 v191, v157
	v_rcp_iflag_f32_e32 v192, v192
	v_rcp_iflag_f32_e32 v193, v193
	v_rcp_iflag_f32_e32 v194, v194
	v_rcp_iflag_f32_e32 v195, v195
	v_cvt_f32_ubyte3_e32 v197, v186
	v_cvt_f32_ubyte2_e32 v196, v186
	v_cvt_f32_ubyte1_e32 v199, v186
	v_cvt_f32_ubyte0_e32 v198, v186
	v_pk_mul_f32 v[188:189], v[188:189], v[198:199]
	v_pk_mul_f32 v[190:191], v[190:191], v[196:197]
	v_pk_mul_f32 v[34:35], v[34:35], v[188:189]
	v_pk_mul_f32 v[36:37], v[36:37], v[190:191]
	v_cvt_f32_ubyte3_e32 v189, v187
	v_cvt_f32_ubyte2_e32 v188, v187
	v_cvt_f32_ubyte1_e32 v191, v187
	v_cvt_f32_ubyte0_e32 v190, v187
	v_pk_mul_f32 v[186:187], v[192:193], v[190:191]
	v_pk_mul_f32 v[188:189], v[194:195], v[188:189]
	s_waitcnt vmcnt(4)
	v_cvt_f32_ubyte0_e32 v3, v184
	v_cvt_f32_ubyte1_e32 v153, v184
	v_cvt_f32_ubyte2_e32 v155, v184
	v_cvt_f32_ubyte3_e32 v157, v184
	v_pk_mul_f32 v[28:29], v[28:29], v[188:189]
	v_pk_mul_f32 v[26:27], v[26:27], v[186:187]
	v_cvt_f32_ubyte0_e32 v188, v185
	v_cvt_f32_ubyte1_e32 v189, v185
	v_cvt_f32_ubyte2_e32 v190, v185
	v_cvt_f32_ubyte3_e32 v191, v185
	v_rcp_iflag_f32_e32 v184, v3
	v_rcp_iflag_f32_e32 v185, v153
	v_rcp_iflag_f32_e32 v186, v155
	v_rcp_iflag_f32_e32 v187, v157
	v_rcp_iflag_f32_e32 v188, v188
	v_rcp_iflag_f32_e32 v189, v189
	v_rcp_iflag_f32_e32 v190, v190
	v_rcp_iflag_f32_e32 v191, v191
	v_cvt_f32_ubyte3_e32 v193, v182
	v_cvt_f32_ubyte2_e32 v192, v182
	v_cvt_f32_ubyte1_e32 v195, v182
	v_cvt_f32_ubyte0_e32 v194, v182
	v_pk_mul_f32 v[184:185], v[184:185], v[194:195]
	v_pk_mul_f32 v[186:187], v[186:187], v[192:193]
	v_pk_mul_f32 v[30:31], v[30:31], v[184:185]
	v_pk_mul_f32 v[32:33], v[32:33], v[186:187]
	v_cvt_f32_ubyte3_e32 v185, v183
	v_cvt_f32_ubyte2_e32 v184, v183
	v_cvt_f32_ubyte1_e32 v187, v183
	v_cvt_f32_ubyte0_e32 v186, v183
	v_pk_mul_f32 v[182:183], v[188:189], v[186:187]
	v_pk_mul_f32 v[184:185], v[190:191], v[184:185]
	s_waitcnt vmcnt(2)
	v_cvt_f32_ubyte0_e32 v3, v180
	v_cvt_f32_ubyte1_e32 v153, v180
	v_cvt_f32_ubyte2_e32 v155, v180
	v_cvt_f32_ubyte3_e32 v157, v180
	v_pk_mul_f32 v[24:25], v[24:25], v[184:185]
	v_pk_mul_f32 v[22:23], v[22:23], v[182:183]
	v_cvt_f32_ubyte0_e32 v184, v181
	v_cvt_f32_ubyte1_e32 v185, v181
	v_cvt_f32_ubyte2_e32 v186, v181
	v_cvt_f32_ubyte3_e32 v187, v181
	v_rcp_iflag_f32_e32 v180, v3
	v_rcp_iflag_f32_e32 v181, v153
	v_rcp_iflag_f32_e32 v182, v155
	v_rcp_iflag_f32_e32 v183, v157
	v_rcp_iflag_f32_e32 v184, v184
	v_rcp_iflag_f32_e32 v185, v185
	v_rcp_iflag_f32_e32 v186, v186
	v_rcp_iflag_f32_e32 v187, v187
	v_cvt_f32_ubyte3_e32 v189, v178
	v_cvt_f32_ubyte2_e32 v188, v178
	v_cvt_f32_ubyte1_e32 v191, v178
	v_cvt_f32_ubyte0_e32 v190, v178
	v_pk_mul_f32 v[180:181], v[180:181], v[190:191]
	v_pk_mul_f32 v[182:183], v[182:183], v[188:189]
	v_pk_mul_f32 v[18:19], v[18:19], v[180:181]
	v_pk_mul_f32 v[20:21], v[20:21], v[182:183]
	v_cvt_f32_ubyte3_e32 v181, v179
	v_cvt_f32_ubyte2_e32 v180, v179
	v_cvt_f32_ubyte1_e32 v183, v179
	v_cvt_f32_ubyte0_e32 v182, v179
	v_pk_mul_f32 v[178:179], v[184:185], v[182:183]
	v_pk_mul_f32 v[180:181], v[186:187], v[180:181]
	s_waitcnt vmcnt(0)
	v_cvt_f32_ubyte0_e32 v3, v176
	v_cvt_f32_ubyte1_e32 v153, v176
	v_cvt_f32_ubyte2_e32 v155, v176
	v_cvt_f32_ubyte3_e32 v157, v176
	v_pk_mul_f32 v[12:13], v[12:13], v[180:181]
	v_pk_mul_f32 v[10:11], v[10:11], v[178:179]
	v_cvt_f32_ubyte0_e32 v180, v177
	v_cvt_f32_ubyte1_e32 v181, v177
	v_cvt_f32_ubyte2_e32 v182, v177
	v_cvt_f32_ubyte3_e32 v183, v177
	v_rcp_iflag_f32_e32 v176, v3
	v_rcp_iflag_f32_e32 v177, v153
	v_rcp_iflag_f32_e32 v178, v155
	v_rcp_iflag_f32_e32 v179, v157
	v_rcp_iflag_f32_e32 v180, v180
	v_rcp_iflag_f32_e32 v181, v181
	v_rcp_iflag_f32_e32 v182, v182
	v_rcp_iflag_f32_e32 v183, v183
	v_cvt_f32_ubyte3_e32 v185, v4
	v_cvt_f32_ubyte2_e32 v184, v4
	v_cvt_f32_ubyte1_e32 v187, v4
	v_cvt_f32_ubyte0_e32 v186, v4
	v_pk_mul_f32 v[176:177], v[176:177], v[186:187]
	v_pk_mul_f32 v[178:179], v[178:179], v[184:185]
	v_pk_mul_f32 v[14:15], v[14:15], v[176:177]
	v_pk_mul_f32 v[16:17], v[16:17], v[178:179]
	v_cvt_f32_ubyte3_e32 v177, v5
	v_cvt_f32_ubyte2_e32 v176, v5
	v_cvt_f32_ubyte1_e32 v179, v5
	v_cvt_f32_ubyte0_e32 v178, v5
	v_pk_mul_f32 v[4:5], v[180:181], v[178:179]
	v_pk_mul_f32 v[176:177], v[182:183], v[176:177]
	v_pk_mul_f32 v[6:7], v[6:7], v[4:5]
	v_pk_mul_f32 v[8:9], v[8:9], v[176:177]

.LBB0_1290:
	s_cmp_lg_u32 s33, 1
	s_mov_b64 s[56:57], -1
	s_cbranch_scc0 .LBB0_1292
	s_lshl_b32 s0, s0, 8
	v_or_b32_e32 v4, s0, v207
	v_mov_b64_e32 v[158:159], s[18:19]
	v_ashrrev_i32_e32 v5, 31, v4
	v_mad_i64_i32 v[160:161], s[56:57], v154, s88, v[158:159]
	v_lshl_add_u64 v[160:161], v[160:161], 0, v[4:5]
	v_lshl_add_u64 v[162:163], v[160:161], 0, s[30:31]
	v_add_co_u32_e32 v160, vcc, 0x2000, v160
	v_ashrrev_i32_e32 v155, 31, v154
	s_nop 0
	v_addc_co_u32_e32 v161, vcc, 0, v161, vcc
	global_load_dwordx2 v[160:161], v[160:161], off nt
	s_ashr_i32 s1, s0, 31
	s_lshl_b64 s[0:1], s[0:1], 1
	s_mov_b32 s39, s15
	v_mov_b32_e32 v153, v2
	s_waitcnt vmcnt(0)
	v_cvt_f32_ubyte3_e32 v171, v161
	v_cvt_f32_ubyte2_e32 v170, v161
	v_cvt_f32_ubyte1_e32 v165, v160
	v_cvt_f32_ubyte0_e32 v164, v160
	v_cvt_f32_ubyte1_e32 v167, v161
	v_cvt_f32_ubyte0_e32 v166, v161
	v_cvt_f32_ubyte3_e32 v169, v160
	v_cvt_f32_ubyte2_e32 v168, v160
	v_pk_mul_f32 v[160:161], v[170:171], s[36:37] op_sel_hi:[1,0]
	v_pk_mul_f32 v[164:165], v[164:165], s[36:37] op_sel_hi:[1,0]
	v_pk_mul_f32 v[170:171], v[116:117], v[160:161]
	global_load_dwordx2 v[160:161], v[162:163], off offset:128 nt
	v_pk_mul_f32 v[166:167], v[166:167], s[36:37] op_sel_hi:[1,0]
	v_pk_mul_f32 v[168:169], v[168:169], s[36:37] op_sel_hi:[1,0]
	v_pk_mul_f32 v[164:165], v[106:107], v[164:165]
	v_pk_mul_f32 v[166:167], v[114:115], v[166:167]
	v_pk_mul_f32 v[168:169], v[108:109], v[168:169]
	s_waitcnt vmcnt(0)
	v_cvt_f32_ubyte1_e32 v163, v160
	v_cvt_f32_ubyte0_e32 v162, v160
	v_pk_mul_f32 v[162:163], v[162:163], s[36:37] op_sel_hi:[1,0]
	s_nop 0
	v_pk_mul_f32 v[172:173], v[126:127], v[162:163]
	v_cvt_f32_ubyte1_e32 v163, v161
	v_cvt_f32_ubyte0_e32 v162, v161
	v_pk_mul_f32 v[162:163], v[162:163], s[36:37] op_sel_hi:[1,0]
	s_nop 0
	v_pk_mul_f32 v[174:175], v[130:131], v[162:163]
	v_cvt_f32_ubyte3_e32 v163, v160
	v_cvt_f32_ubyte2_e32 v162, v160
	v_pk_mul_f32 v[162:163], v[162:163], s[36:37] op_sel_hi:[1,0]
	s_nop 0
	v_pk_mul_f32 v[176:177], v[128:129], v[162:163]
	v_cvt_f32_ubyte3_e32 v163, v161
	v_cvt_f32_ubyte2_e32 v162, v161
	v_pk_mul_f32 v[160:161], v[162:163], s[36:37] op_sel_hi:[1,0]
	v_cvt_pk_bf16_f32 v162, v166, v167
	v_pk_mul_f32 v[178:179], v[132:133], v[160:161]
	v_lshlrev_b64 v[160:161], 13, v[154:155]
	v_lshl_add_u64 v[160:161], s[4:5], 0, v[160:161]
	v_lshl_add_u64 v[160:161], v[160:161], 0, s[0:1]
	v_lshl_add_u64 v[160:161], v[160:161], 0, s[38:39]
	v_lshl_add_u64 v[180:181], v[160:161], 0, v[152:153]
	v_cvt_pk_bf16_f32 v160, v164, v165
	v_cvt_pk_bf16_f32 v161, v168, v169
	v_cvt_pk_bf16_f32 v163, v170, v171
	global_store_dwordx4 v[180:181], v[160:163], off
	s_nop 1
	v_cvt_pk_bf16_f32 v160, v172, v173
	v_cvt_pk_bf16_f32 v161, v176, v177
	v_cvt_pk_bf16_f32 v162, v174, v175
	v_cvt_pk_bf16_f32 v163, v178, v179
	global_store_dwordx4 v[180:181], v[160:163], off offset:256
	s_nop 1
	v_or_b32_e32 v160, 16, v154
	v_mad_i64_i32 v[162:163], s[56:57], v160, s88, v[158:159]
	v_lshl_add_u64 v[162:163], v[162:163], 0, v[4:5]
	v_lshl_add_u64 v[164:165], v[162:163], 0, s[30:31]
	v_add_co_u32_e32 v162, vcc, s75, v162
	v_ashrrev_i32_e32 v161, 31, v160
	s_nop 0
	v_addc_co_u32_e32 v163, vcc, 0, v163, vcc
	global_load_dwordx2 v[162:163], v[162:163], off nt
	v_lshlrev_b64 v[160:161], 13, v[160:161]
	v_lshl_add_u64 v[160:161], s[4:5], 0, v[160:161]
	v_lshl_add_u64 v[160:161], v[160:161], 0, s[0:1]
	v_lshl_add_u64 v[160:161], v[160:161], 0, s[38:39]
	v_lshl_add_u64 v[180:181], v[160:161], 0, v[152:153]
	s_waitcnt vmcnt(0)
	v_cvt_f32_ubyte3_e32 v173, v163
	v_cvt_f32_ubyte2_e32 v172, v163
	v_cvt_f32_ubyte1_e32 v167, v162
	v_cvt_f32_ubyte0_e32 v166, v162
	v_cvt_f32_ubyte1_e32 v169, v163
	v_cvt_f32_ubyte0_e32 v168, v163
	v_cvt_f32_ubyte3_e32 v171, v162
	v_cvt_f32_ubyte2_e32 v170, v162
	v_pk_mul_f32 v[162:163], v[172:173], s[36:37] op_sel_hi:[1,0]
	v_pk_mul_f32 v[166:167], v[166:167], s[36:37] op_sel_hi:[1,0]
	v_pk_mul_f32 v[172:173], v[112:113], v[162:163]
	global_load_dwordx2 v[162:163], v[164:165], off offset:128 nt
	v_pk_mul_f32 v[168:169], v[168:169], s[36:37] op_sel_hi:[1,0]
	v_pk_mul_f32 v[170:171], v[170:171], s[36:37] op_sel_hi:[1,0]
	v_pk_mul_f32 v[166:167], v[102:103], v[166:167]
	v_pk_mul_f32 v[168:169], v[110:111], v[168:169]
	v_pk_mul_f32 v[170:171], v[104:105], v[170:171]
	v_cvt_pk_bf16_f32 v160, v166, v167
	v_cvt_pk_bf16_f32 v161, v170, v171
	s_waitcnt vmcnt(0)
	v_cvt_f32_ubyte1_e32 v165, v162
	v_cvt_f32_ubyte0_e32 v164, v162
	v_cvt_f32_ubyte1_e32 v175, v163
	v_cvt_f32_ubyte0_e32 v174, v163
	v_cvt_f32_ubyte3_e32 v177, v162
	v_cvt_f32_ubyte2_e32 v176, v162
	v_cvt_f32_ubyte3_e32 v179, v163
	v_cvt_f32_ubyte2_e32 v178, v163
	v_pk_mul_f32 v[164:165], v[164:165], s[36:37] op_sel_hi:[1,0]
	v_pk_mul_f32 v[174:175], v[174:175], s[36:37] op_sel_hi:[1,0]
	v_pk_mul_f32 v[176:177], v[176:177], s[36:37] op_sel_hi:[1,0]
	v_pk_mul_f32 v[162:163], v[178:179], s[36:37] op_sel_hi:[1,0]
	v_pk_mul_f32 v[164:165], v[122:123], v[164:165]
	v_pk_mul_f32 v[174:175], v[118:119], v[174:175]
	v_pk_mul_f32 v[176:177], v[124:125], v[176:177]
	v_pk_mul_f32 v[178:179], v[120:121], v[162:163]
	v_cvt_pk_bf16_f32 v162, v168, v169
	v_cvt_pk_bf16_f32 v163, v172, v173
	global_store_dwordx4 v[180:181], v[160:163], off
	s_nop 1
	v_cvt_pk_bf16_f32 v160, v164, v165
	v_cvt_pk_bf16_f32 v161, v176, v177
	v_cvt_pk_bf16_f32 v162, v174, v175
	v_cvt_pk_bf16_f32 v163, v178, v179
	global_store_dwordx4 v[180:181], v[160:163], off offset:256
	s_nop 1
	v_or_b32_e32 v160, 32, v154
	v_mad_i64_i32 v[162:163], s[56:57], v160, s88, v[158:159]
	v_lshl_add_u64 v[162:163], v[162:163], 0, v[4:5]
	v_lshl_add_u64 v[164:165], v[162:163], 0, s[30:31]
	v_add_co_u32_e32 v162, vcc, s75, v162
	v_ashrrev_i32_e32 v161, 31, v160
	s_nop 0
	v_addc_co_u32_e32 v163, vcc, 0, v163, vcc
	global_load_dwordx2 v[162:163], v[162:163], off nt
	v_lshlrev_b64 v[160:161], 13, v[160:161]
	v_lshl_add_u64 v[160:161], s[4:5], 0, v[160:161]
	v_lshl_add_u64 v[160:161], v[160:161], 0, s[0:1]
	v_lshl_add_u64 v[160:161], v[160:161], 0, s[38:39]
	v_lshl_add_u64 v[180:181], v[160:161], 0, v[152:153]
	s_waitcnt vmcnt(0)
	v_cvt_f32_ubyte3_e32 v173, v163
	v_cvt_f32_ubyte2_e32 v172, v163
	v_cvt_f32_ubyte1_e32 v167, v162
	v_cvt_f32_ubyte0_e32 v166, v162
	v_cvt_f32_ubyte1_e32 v169, v163
	v_cvt_f32_ubyte0_e32 v168, v163
	v_cvt_f32_ubyte3_e32 v171, v162
	v_cvt_f32_ubyte2_e32 v170, v162
	v_pk_mul_f32 v[162:163], v[172:173], s[36:37] op_sel_hi:[1,0]
	v_pk_mul_f32 v[166:167], v[166:167], s[36:37] op_sel_hi:[1,0]
	v_pk_mul_f32 v[172:173], v[88:89], v[162:163]
	global_load_dwordx2 v[162:163], v[164:165], off offset:128 nt
	v_pk_mul_f32 v[168:169], v[168:169], s[36:37] op_sel_hi:[1,0]
	v_pk_mul_f32 v[170:171], v[170:171], s[36:37] op_sel_hi:[1,0]
	v_pk_mul_f32 v[166:167], v[90:91], v[166:167]
	v_pk_mul_f32 v[168:169], v[86:87], v[168:169]
	v_pk_mul_f32 v[170:171], v[92:93], v[170:171]
	v_cvt_pk_bf16_f32 v160, v166, v167
	v_cvt_pk_bf16_f32 v161, v170, v171
	s_waitcnt vmcnt(0)
	v_cvt_f32_ubyte1_e32 v165, v162
	v_cvt_f32_ubyte0_e32 v164, v162
	v_cvt_f32_ubyte1_e32 v175, v163
	v_cvt_f32_ubyte0_e32 v174, v163
	v_cvt_f32_ubyte3_e32 v177, v162
	v_cvt_f32_ubyte2_e32 v176, v162
	v_cvt_f32_ubyte3_e32 v179, v163
	v_cvt_f32_ubyte2_e32 v178, v163
	v_pk_mul_f32 v[164:165], v[164:165], s[36:37] op_sel_hi:[1,0]
	v_pk_mul_f32 v[174:175], v[174:175], s[36:37] op_sel_hi:[1,0]
	v_pk_mul_f32 v[176:177], v[176:177], s[36:37] op_sel_hi:[1,0]
	v_pk_mul_f32 v[162:163], v[178:179], s[36:37] op_sel_hi:[1,0]
	v_pk_mul_f32 v[164:165], v[98:99], v[164:165]
	v_pk_mul_f32 v[174:175], v[94:95], v[174:175]
	v_pk_mul_f32 v[176:177], v[100:101], v[176:177]
	v_pk_mul_f32 v[178:179], v[96:97], v[162:163]
	v_cvt_pk_bf16_f32 v162, v168, v169
	v_cvt_pk_bf16_f32 v163, v172, v173
	global_store_dwordx4 v[180:181], v[160:163], off
	s_nop 1
	v_cvt_pk_bf16_f32 v160, v164, v165
	v_cvt_pk_bf16_f32 v161, v176, v177
	v_cvt_pk_bf16_f32 v162, v174, v175
	v_cvt_pk_bf16_f32 v163, v178, v179
	global_store_dwordx4 v[180:181], v[160:163], off offset:256
	s_nop 1
	v_or_b32_e32 v160, 48, v154
	v_mad_i64_i32 v[162:163], s[56:57], v160, s88, v[158:159]
	v_lshl_add_u64 v[162:163], v[162:163], 0, v[4:5]
	v_lshl_add_u64 v[164:165], v[162:163], 0, s[30:31]
	v_add_co_u32_e32 v162, vcc, s75, v162
	v_ashrrev_i32_e32 v161, 31, v160
	s_nop 0
	v_addc_co_u32_e32 v163, vcc, 0, v163, vcc
	global_load_dwordx2 v[162:163], v[162:163], off nt
	v_lshlrev_b64 v[160:161], 13, v[160:161]
	v_lshl_add_u64 v[160:161], s[4:5], 0, v[160:161]
	v_lshl_add_u64 v[160:161], v[160:161], 0, s[0:1]
	v_lshl_add_u64 v[160:161], v[160:161], 0, s[38:39]
	v_lshl_add_u64 v[180:181], v[160:161], 0, v[152:153]
	s_waitcnt vmcnt(0)
	v_cvt_f32_ubyte3_e32 v173, v163
	v_cvt_f32_ubyte2_e32 v172, v163
	v_cvt_f32_ubyte1_e32 v167, v162
	v_cvt_f32_ubyte0_e32 v166, v162
	v_cvt_f32_ubyte1_e32 v169, v163
	v_cvt_f32_ubyte0_e32 v168, v163
	v_cvt_f32_ubyte3_e32 v171, v162
	v_cvt_f32_ubyte2_e32 v170, v162
	v_pk_mul_f32 v[162:163], v[172:173], s[36:37] op_sel_hi:[1,0]
	v_pk_mul_f32 v[166:167], v[166:167], s[36:37] op_sel_hi:[1,0]
	v_pk_mul_f32 v[172:173], v[72:73], v[162:163]
	global_load_dwordx2 v[162:163], v[164:165], off offset:128 nt
	v_pk_mul_f32 v[168:169], v[168:169], s[36:37] op_sel_hi:[1,0]
	v_pk_mul_f32 v[170:171], v[170:171], s[36:37] op_sel_hi:[1,0]
	v_pk_mul_f32 v[166:167], v[74:75], v[166:167]
	v_pk_mul_f32 v[168:169], v[70:71], v[168:169]
	v_pk_mul_f32 v[170:171], v[76:77], v[170:171]
	v_cvt_pk_bf16_f32 v160, v166, v167
	v_cvt_pk_bf16_f32 v161, v170, v171
	s_waitcnt vmcnt(0)
	v_cvt_f32_ubyte1_e32 v165, v162
	v_cvt_f32_ubyte0_e32 v164, v162
	v_cvt_f32_ubyte1_e32 v175, v163
	v_cvt_f32_ubyte0_e32 v174, v163
	v_cvt_f32_ubyte3_e32 v177, v162
	v_cvt_f32_ubyte2_e32 v176, v162
	v_cvt_f32_ubyte3_e32 v179, v163
	v_cvt_f32_ubyte2_e32 v178, v163
	v_pk_mul_f32 v[164:165], v[164:165], s[36:37] op_sel_hi:[1,0]
	v_pk_mul_f32 v[174:175], v[174:175], s[36:37] op_sel_hi:[1,0]
	v_pk_mul_f32 v[176:177], v[176:177], s[36:37] op_sel_hi:[1,0]
	v_pk_mul_f32 v[162:163], v[178:179], s[36:37] op_sel_hi:[1,0]
	v_pk_mul_f32 v[164:165], v[82:83], v[164:165]
	v_pk_mul_f32 v[174:175], v[78:79], v[174:175]
	v_pk_mul_f32 v[176:177], v[84:85], v[176:177]
	v_pk_mul_f32 v[178:179], v[80:81], v[162:163]
	v_cvt_pk_bf16_f32 v162, v168, v169
	v_cvt_pk_bf16_f32 v163, v172, v173
	global_store_dwordx4 v[180:181], v[160:163], off
	s_nop 1
	v_cvt_pk_bf16_f32 v160, v164, v165
	v_cvt_pk_bf16_f32 v161, v176, v177
	v_cvt_pk_bf16_f32 v162, v174, v175
	v_cvt_pk_bf16_f32 v163, v178, v179
	global_store_dwordx4 v[180:181], v[160:163], off offset:256
	s_nop 1
	v_add_u32_e32 v160, 0x80, v154
	v_mad_i64_i32 v[162:163], s[56:57], v160, s88, v[158:159]
	v_lshl_add_u64 v[162:163], v[162:163], 0, v[4:5]
	v_lshl_add_u64 v[164:165], v[162:163], 0, s[30:31]
	v_add_co_u32_e32 v162, vcc, s75, v162
	v_ashrrev_i32_e32 v161, 31, v160
	s_nop 0
	v_addc_co_u32_e32 v163, vcc, 0, v163, vcc
	global_load_dwordx2 v[162:163], v[162:163], off nt
	v_lshlrev_b64 v[160:161], 13, v[160:161]
	v_lshl_add_u64 v[160:161], s[4:5], 0, v[160:161]
	v_lshl_add_u64 v[160:161], v[160:161], 0, s[0:1]
	v_lshl_add_u64 v[160:161], v[160:161], 0, s[38:39]
	v_lshl_add_u64 v[180:181], v[160:161], 0, v[152:153]
	s_waitcnt vmcnt(0)
	v_cvt_f32_ubyte3_e32 v173, v163
	v_cvt_f32_ubyte2_e32 v172, v163
	v_cvt_f32_ubyte1_e32 v167, v162
	v_cvt_f32_ubyte0_e32 v166, v162
	v_cvt_f32_ubyte1_e32 v169, v163
	v_cvt_f32_ubyte0_e32 v168, v163
	v_cvt_f32_ubyte3_e32 v171, v162
	v_cvt_f32_ubyte2_e32 v170, v162
	v_pk_mul_f32 v[162:163], v[172:173], s[36:37] op_sel_hi:[1,0]
	v_pk_mul_f32 v[166:167], v[166:167], s[36:37] op_sel_hi:[1,0]
	v_pk_mul_f32 v[172:173], v[60:61], v[162:163]
	global_load_dwordx2 v[162:163], v[164:165], off offset:128 nt
	v_pk_mul_f32 v[168:169], v[168:169], s[36:37] op_sel_hi:[1,0]
	v_pk_mul_f32 v[170:171], v[170:171], s[36:37] op_sel_hi:[1,0]
	v_pk_mul_f32 v[166:167], v[66:67], v[166:167]
	v_pk_mul_f32 v[168:169], v[58:59], v[168:169]
	v_pk_mul_f32 v[170:171], v[68:69], v[170:171]
	v_cvt_pk_bf16_f32 v160, v166, v167
	v_cvt_pk_bf16_f32 v161, v170, v171
	s_waitcnt vmcnt(0)
	v_cvt_f32_ubyte1_e32 v165, v162
	v_cvt_f32_ubyte0_e32 v164, v162
	v_cvt_f32_ubyte1_e32 v175, v163
	v_cvt_f32_ubyte0_e32 v174, v163
	v_cvt_f32_ubyte3_e32 v177, v162
	v_cvt_f32_ubyte2_e32 v176, v162
	v_cvt_f32_ubyte3_e32 v179, v163
	v_cvt_f32_ubyte2_e32 v178, v163
	v_pk_mul_f32 v[164:165], v[164:165], s[36:37] op_sel_hi:[1,0]
	v_pk_mul_f32 v[174:175], v[174:175], s[36:37] op_sel_hi:[1,0]
	v_pk_mul_f32 v[176:177], v[176:177], s[36:37] op_sel_hi:[1,0]
	v_pk_mul_f32 v[162:163], v[178:179], s[36:37] op_sel_hi:[1,0]
	v_pk_mul_f32 v[164:165], v[62:63], v[164:165]
	v_pk_mul_f32 v[174:175], v[54:55], v[174:175]
	v_pk_mul_f32 v[176:177], v[64:65], v[176:177]
	v_pk_mul_f32 v[178:179], v[56:57], v[162:163]
	v_cvt_pk_bf16_f32 v162, v168, v169
	v_cvt_pk_bf16_f32 v163, v172, v173
	global_store_dwordx4 v[180:181], v[160:163], off
	s_nop 1
	v_cvt_pk_bf16_f32 v160, v164, v165
	v_cvt_pk_bf16_f32 v161, v176, v177
	v_cvt_pk_bf16_f32 v162, v174, v175
	v_cvt_pk_bf16_f32 v163, v178, v179
	global_store_dwordx4 v[180:181], v[160:163], off offset:256
	s_nop 1
	v_add_u32_e32 v160, 0x90, v154
	v_mad_i64_i32 v[162:163], s[56:57], v160, s88, v[158:159]
	v_lshl_add_u64 v[162:163], v[162:163], 0, v[4:5]
	v_lshl_add_u64 v[164:165], v[162:163], 0, s[30:31]
	v_add_co_u32_e32 v162, vcc, s75, v162
	v_ashrrev_i32_e32 v161, 31, v160
	s_nop 0
	v_addc_co_u32_e32 v163, vcc, 0, v163, vcc
	global_load_dwordx2 v[162:163], v[162:163], off nt
	v_lshlrev_b64 v[160:161], 13, v[160:161]
	v_lshl_add_u64 v[160:161], s[4:5], 0, v[160:161]
	v_lshl_add_u64 v[160:161], v[160:161], 0, s[0:1]
	v_lshl_add_u64 v[160:161], v[160:161], 0, s[38:39]
	v_lshl_add_u64 v[180:181], v[160:161], 0, v[152:153]
	s_waitcnt vmcnt(0)
	v_cvt_f32_ubyte3_e32 v173, v163
	v_cvt_f32_ubyte2_e32 v172, v163
	v_cvt_f32_ubyte1_e32 v167, v162
	v_cvt_f32_ubyte0_e32 v166, v162
	v_cvt_f32_ubyte1_e32 v169, v163
	v_cvt_f32_ubyte0_e32 v168, v163
	v_cvt_f32_ubyte3_e32 v171, v162
	v_cvt_f32_ubyte2_e32 v170, v162
	v_pk_mul_f32 v[162:163], v[172:173], s[36:37] op_sel_hi:[1,0]
	v_pk_mul_f32 v[166:167], v[166:167], s[36:37] op_sel_hi:[1,0]
	v_pk_mul_f32 v[172:173], v[44:45], v[162:163]
	global_load_dwordx2 v[162:163], v[164:165], off offset:128 nt
	v_pk_mul_f32 v[168:169], v[168:169], s[36:37] op_sel_hi:[1,0]
	v_pk_mul_f32 v[170:171], v[170:171], s[36:37] op_sel_hi:[1,0]
	v_pk_mul_f32 v[166:167], v[50:51], v[166:167]
	v_pk_mul_f32 v[168:169], v[42:43], v[168:169]
	v_pk_mul_f32 v[170:171], v[52:53], v[170:171]
	v_cvt_pk_bf16_f32 v160, v166, v167
	v_cvt_pk_bf16_f32 v161, v170, v171
	s_waitcnt vmcnt(0)
	v_cvt_f32_ubyte1_e32 v165, v162
	v_cvt_f32_ubyte0_e32 v164, v162
	v_cvt_f32_ubyte1_e32 v175, v163
	v_cvt_f32_ubyte0_e32 v174, v163
	v_cvt_f32_ubyte3_e32 v177, v162
	v_cvt_f32_ubyte2_e32 v176, v162
	v_cvt_f32_ubyte3_e32 v179, v163
	v_cvt_f32_ubyte2_e32 v178, v163
	v_pk_mul_f32 v[164:165], v[164:165], s[36:37] op_sel_hi:[1,0]
	v_pk_mul_f32 v[174:175], v[174:175], s[36:37] op_sel_hi:[1,0]
	v_pk_mul_f32 v[176:177], v[176:177], s[36:37] op_sel_hi:[1,0]
	v_pk_mul_f32 v[162:163], v[178:179], s[36:37] op_sel_hi:[1,0]
	v_pk_mul_f32 v[164:165], v[46:47], v[164:165]
	v_pk_mul_f32 v[174:175], v[38:39], v[174:175]
	v_pk_mul_f32 v[176:177], v[48:49], v[176:177]
	v_pk_mul_f32 v[178:179], v[40:41], v[162:163]
	v_cvt_pk_bf16_f32 v162, v168, v169
	v_cvt_pk_bf16_f32 v163, v172, v173
	global_store_dwordx4 v[180:181], v[160:163], off
	s_nop 1
	v_cvt_pk_bf16_f32 v160, v164, v165
	v_cvt_pk_bf16_f32 v161, v176, v177
	v_cvt_pk_bf16_f32 v162, v174, v175
	v_cvt_pk_bf16_f32 v163, v178, v179
	global_store_dwordx4 v[180:181], v[160:163], off offset:256
	s_nop 1
	v_add_u32_e32 v160, 0xa0, v154
	v_mad_i64_i32 v[162:163], s[56:57], v160, s88, v[158:159]
	v_lshl_add_u64 v[162:163], v[162:163], 0, v[4:5]
	v_lshl_add_u64 v[164:165], v[162:163], 0, s[30:31]
	v_add_co_u32_e32 v162, vcc, s75, v162
	v_ashrrev_i32_e32 v161, 31, v160
	s_nop 0
	v_addc_co_u32_e32 v163, vcc, 0, v163, vcc
	global_load_dwordx2 v[162:163], v[162:163], off nt
	v_lshlrev_b64 v[160:161], 13, v[160:161]
	v_lshl_add_u64 v[160:161], s[4:5], 0, v[160:161]
	v_lshl_add_u64 v[160:161], v[160:161], 0, s[0:1]
	v_lshl_add_u64 v[160:161], v[160:161], 0, s[38:39]
	v_lshl_add_u64 v[180:181], v[160:161], 0, v[152:153]
	s_waitcnt vmcnt(0)
	v_cvt_f32_ubyte3_e32 v173, v163
	v_cvt_f32_ubyte2_e32 v172, v163
	v_cvt_f32_ubyte1_e32 v167, v162
	v_cvt_f32_ubyte0_e32 v166, v162
	v_cvt_f32_ubyte1_e32 v169, v163
	v_cvt_f32_ubyte0_e32 v168, v163
	v_cvt_f32_ubyte3_e32 v171, v162
	v_cvt_f32_ubyte2_e32 v170, v162
	v_pk_mul_f32 v[162:163], v[172:173], s[36:37] op_sel_hi:[1,0]
	v_pk_mul_f32 v[166:167], v[166:167], s[36:37] op_sel_hi:[1,0]
	v_pk_mul_f32 v[172:173], v[28:29], v[162:163]
	global_load_dwordx2 v[162:163], v[164:165], off offset:128 nt
	v_pk_mul_f32 v[168:169], v[168:169], s[36:37] op_sel_hi:[1,0]
	v_pk_mul_f32 v[170:171], v[170:171], s[36:37] op_sel_hi:[1,0]
	v_pk_mul_f32 v[166:167], v[34:35], v[166:167]
	v_pk_mul_f32 v[168:169], v[26:27], v[168:169]
	v_pk_mul_f32 v[170:171], v[36:37], v[170:171]
	v_cvt_pk_bf16_f32 v160, v166, v167
	v_cvt_pk_bf16_f32 v161, v170, v171
	s_waitcnt vmcnt(0)
	v_cvt_f32_ubyte1_e32 v165, v162
	v_cvt_f32_ubyte0_e32 v164, v162
	v_cvt_f32_ubyte1_e32 v175, v163
	v_cvt_f32_ubyte0_e32 v174, v163
	v_cvt_f32_ubyte3_e32 v177, v162
	v_cvt_f32_ubyte2_e32 v176, v162
	v_cvt_f32_ubyte3_e32 v179, v163
	v_cvt_f32_ubyte2_e32 v178, v163
	v_pk_mul_f32 v[164:165], v[164:165], s[36:37] op_sel_hi:[1,0]
	v_pk_mul_f32 v[174:175], v[174:175], s[36:37] op_sel_hi:[1,0]
	v_pk_mul_f32 v[176:177], v[176:177], s[36:37] op_sel_hi:[1,0]
	v_pk_mul_f32 v[162:163], v[178:179], s[36:37] op_sel_hi:[1,0]
	v_pk_mul_f32 v[164:165], v[30:31], v[164:165]
	v_pk_mul_f32 v[174:175], v[22:23], v[174:175]
	v_pk_mul_f32 v[176:177], v[32:33], v[176:177]
	v_pk_mul_f32 v[178:179], v[24:25], v[162:163]
	v_cvt_pk_bf16_f32 v162, v168, v169
	v_cvt_pk_bf16_f32 v163, v172, v173
	global_store_dwordx4 v[180:181], v[160:163], off
	s_nop 1
	v_cvt_pk_bf16_f32 v160, v164, v165
	v_cvt_pk_bf16_f32 v161, v176, v177
	v_cvt_pk_bf16_f32 v162, v174, v175
	v_cvt_pk_bf16_f32 v163, v178, v179
	global_store_dwordx4 v[180:181], v[160:163], off offset:256
	s_nop 1
	v_add_u32_e32 v160, 0xb0, v154
	v_mad_i64_i32 v[158:159], s[56:57], v160, s88, v[158:159]
	v_lshl_add_u64 v[4:5], v[158:159], 0, v[4:5]
	v_lshl_add_u64 v[162:163], v[4:5], 0, s[30:31]
	v_add_co_u32_e32 v4, vcc, s75, v4
	global_load_dwordx2 v[162:163], v[162:163], off offset:128 nt
	s_nop 0
	v_addc_co_u32_e32 v5, vcc, 0, v5, vcc
	global_load_dwordx2 v[164:165], v[4:5], off nt
	v_ashrrev_i32_e32 v161, 31, v160
	v_lshlrev_b64 v[160:161], 13, v[160:161]
	v_lshl_add_u64 v[160:161], s[4:5], 0, v[160:161]
	v_lshl_add_u64 v[160:161], v[160:161], 0, s[0:1]
	v_lshl_add_u64 v[160:161], v[160:161], 0, s[38:39]
	v_lshl_add_u64 v[176:177], v[160:161], 0, v[152:153]
	s_mov_b64 s[56:57], 0
	s_waitcnt vmcnt(1)
	v_cvt_f32_ubyte1_e32 v171, v163
	v_cvt_f32_ubyte0_e32 v170, v163
	v_cvt_f32_ubyte3_e32 v173, v162
	s_waitcnt vmcnt(0)
	v_cvt_f32_ubyte1_e32 v5, v164
	v_cvt_f32_ubyte0_e32 v4, v164
	v_cvt_f32_ubyte1_e32 v159, v165
	v_cvt_f32_ubyte0_e32 v158, v165
	v_cvt_f32_ubyte3_e32 v167, v164
	v_cvt_f32_ubyte2_e32 v166, v164
	v_cvt_f32_ubyte3_e32 v169, v165
	v_cvt_f32_ubyte2_e32 v168, v165
	v_pk_mul_f32 v[4:5], v[4:5], s[36:37] op_sel_hi:[1,0]
	v_pk_mul_f32 v[158:159], v[158:159], s[36:37] op_sel_hi:[1,0]
	v_pk_mul_f32 v[166:167], v[166:167], s[36:37] op_sel_hi:[1,0]
	v_pk_mul_f32 v[164:165], v[168:169], s[36:37] op_sel_hi:[1,0]
	v_cvt_f32_ubyte1_e32 v169, v162
	v_cvt_f32_ubyte0_e32 v168, v162
	v_cvt_f32_ubyte2_e32 v172, v162
	v_cvt_f32_ubyte3_e32 v175, v163
	v_cvt_f32_ubyte2_e32 v174, v163
	v_pk_mul_f32 v[4:5], v[18:19], v[4:5]
	v_pk_mul_f32 v[158:159], v[10:11], v[158:159]
	v_pk_mul_f32 v[166:167], v[20:21], v[166:167]
	v_pk_mul_f32 v[164:165], v[12:13], v[164:165]
	v_pk_mul_f32 v[168:169], v[168:169], s[36:37] op_sel_hi:[1,0]
	v_pk_mul_f32 v[170:171], v[170:171], s[36:37] op_sel_hi:[1,0]
	v_pk_mul_f32 v[172:173], v[172:173], s[36:37] op_sel_hi:[1,0]
	v_pk_mul_f32 v[162:163], v[174:175], s[36:37] op_sel_hi:[1,0]
	v_pk_mul_f32 v[168:169], v[14:15], v[168:169]
	v_pk_mul_f32 v[170:171], v[6:7], v[170:171]
	v_pk_mul_f32 v[172:173], v[16:17], v[172:173]
	v_pk_mul_f32 v[174:175], v[8:9], v[162:163]
	v_cvt_pk_bf16_f32 v160, v4, v5
	v_cvt_pk_bf16_f32 v161, v166, v167
	v_cvt_pk_bf16_f32 v162, v158, v159
	v_cvt_pk_bf16_f32 v163, v164, v165
	global_store_dwordx4 v[176:177], v[160:163], off
	v_cvt_pk_bf16_f32 v158, v168, v169
	v_cvt_pk_bf16_f32 v159, v172, v173
	v_cvt_pk_bf16_f32 v160, v170, v171
	v_cvt_pk_bf16_f32 v161, v174, v175
	global_store_dwordx4 v[176:177], v[158:161], off offset:256
.LBB0_1292:
	s_andn2_b64 vcc, exec, s[56:57]
	s_cbranch_vccnz .LBB0_1294
	s_cmp_lt_i32 s54, 48
	s_cselect_b32 s0, s89, 0x2000
	s_cmp_gt_i32 s54, 31
	s_cselect_b32 s0, s0, 0
	s_add_u32 s0, s18, s0
	v_ashrrev_i32_e32 v157, 31, v156
	s_addc_u32 s1, s19, 0
	v_lshl_add_u64 v[164:165], s[0:1], 0, v[156:157]
	v_or_b32_e32 v3, 16, v154
	v_mad_i64_i32 v[4:5], s[0:1], v154, s88, v[164:165]
	v_mad_i64_i32 v[158:159], s[0:1], v3, s88, v[164:165]
	global_load_dwordx2 v[156:157], v[4:5], off nt
	s_nop 0
	global_load_dwordx2 v[4:5], v[4:5], off offset:128 nt
	s_nop 0
	global_load_dwordx2 v[160:161], v[158:159], off nt
	s_nop 0
	global_load_dwordx2 v[158:159], v[158:159], off offset:128 nt
	v_or_b32_e32 v3, 32, v154
	v_mad_i64_i32 v[162:163], s[0:1], v3, s88, v[164:165]
	global_load_dwordx2 v[172:173], v[162:163], off nt
	v_or_b32_e32 v3, 48, v154
	v_mad_i64_i32 v[166:167], s[0:1], v3, s88, v[164:165]
	global_load_dwordx2 v[170:171], v[162:163], off offset:128 nt
	global_load_dwordx2 v[168:169], v[166:167], off nt
	s_nop 0
	global_load_dwordx2 v[166:167], v[166:167], off offset:128 nt
	v_add_u32_e32 v3, 0x80, v154
	s_waitcnt vmcnt(0)
	v_cvt_f32_ubyte1_e32 v163, v156
	v_cvt_f32_ubyte0_e32 v162, v156
	v_cvt_f32_ubyte1_e32 v175, v157
	v_cvt_f32_ubyte0_e32 v174, v157
	v_cvt_f32_ubyte3_e32 v177, v156
	v_cvt_f32_ubyte2_e32 v176, v156
	v_cvt_f32_ubyte3_e32 v179, v157
	v_cvt_f32_ubyte2_e32 v178, v157
	v_cvt_f32_ubyte1_e32 v157, v4
	v_cvt_f32_ubyte0_e32 v156, v4
	v_cvt_f32_ubyte1_e32 v181, v5
	v_cvt_f32_ubyte0_e32 v180, v5
	v_cvt_f32_ubyte3_e32 v183, v4
	v_cvt_f32_ubyte2_e32 v182, v4
	v_cvt_f32_ubyte3_e32 v185, v5
	v_cvt_f32_ubyte2_e32 v184, v5
	v_cvt_f32_ubyte1_e32 v5, v160
	v_cvt_f32_ubyte0_e32 v4, v160
	v_cvt_f32_ubyte1_e32 v193, v159
	v_cvt_f32_ubyte0_e32 v192, v159
	v_cvt_f32_ubyte1_e32 v187, v161
	v_cvt_f32_ubyte0_e32 v186, v161
	v_cvt_f32_ubyte3_e32 v189, v160
	v_cvt_f32_ubyte2_e32 v188, v160
	v_cvt_f32_ubyte3_e32 v191, v161
	v_cvt_f32_ubyte2_e32 v190, v161
	v_cvt_f32_ubyte1_e32 v161, v158
	v_cvt_f32_ubyte0_e32 v160, v158
	v_cvt_f32_ubyte3_e32 v195, v158
	v_cvt_f32_ubyte2_e32 v194, v158
	v_cvt_f32_ubyte3_e32 v197, v159
	v_cvt_f32_ubyte2_e32 v196, v159
	v_pk_mul_f32 v[158:159], v[162:163], s[36:37] op_sel_hi:[1,0]
	v_pk_mul_f32 v[162:163], v[174:175], s[36:37] op_sel_hi:[1,0]
	v_pk_mul_f32 v[174:175], v[176:177], s[36:37] op_sel_hi:[1,0]
	v_pk_mul_f32 v[176:177], v[178:179], s[36:37] op_sel_hi:[1,0]
	v_pk_mul_f32 v[182:183], v[182:183], s[36:37] op_sel_hi:[1,0]
	v_pk_mul_f32 v[4:5], v[4:5], s[36:37] op_sel_hi:[1,0]
	v_pk_mul_f32 v[192:193], v[192:193], s[36:37] op_sel_hi:[1,0]
	v_pk_mul_f32 v[198:199], v[160:161], s[36:37] op_sel_hi:[1,0]
	v_pk_mul_f32 v[160:161], v[116:117], v[176:177]
	v_pk_mul_f32 v[116:117], v[128:129], v[182:183]
	v_pk_mul_f32 v[128:129], v[102:103], v[4:5]
	v_pk_mul_f32 v[4:5], v[118:119], v[192:193]
	v_cvt_f32_ubyte1_e32 v119, v172
	v_cvt_f32_ubyte0_e32 v118, v172
	v_pk_mul_f32 v[118:119], v[118:119], s[36:37] op_sel_hi:[1,0]
	v_pk_mul_f32 v[178:179], v[156:157], s[36:37] op_sel_hi:[1,0]
	v_pk_mul_f32 v[118:119], v[90:91], v[118:119]
	v_cvt_f32_ubyte1_e32 v91, v173
	v_cvt_f32_ubyte0_e32 v90, v173
	v_pk_mul_f32 v[186:187], v[186:187], s[36:37] op_sel_hi:[1,0]
	v_pk_mul_f32 v[196:197], v[196:197], s[36:37] op_sel_hi:[1,0]
	v_pk_mul_f32 v[90:91], v[90:91], s[36:37] op_sel_hi:[1,0]
	v_pk_mul_f32 v[156:157], v[114:115], v[162:163]
	v_pk_mul_f32 v[162:163], v[108:109], v[174:175]
	v_pk_mul_f32 v[108:109], v[126:127], v[178:179]
	v_pk_mul_f32 v[126:127], v[110:111], v[186:187]
	v_pk_mul_f32 v[110:111], v[120:121], v[196:197]
	v_pk_mul_f32 v[120:121], v[86:87], v[90:91]
	v_cvt_f32_ubyte3_e32 v87, v172
	v_cvt_f32_ubyte2_e32 v86, v172
	v_pk_mul_f32 v[86:87], v[86:87], s[36:37] op_sel_hi:[1,0]
	v_pk_mul_f32 v[102:103], v[122:123], v[198:199]
	v_pk_mul_f32 v[122:123], v[92:93], v[86:87]
	v_cvt_f32_ubyte3_e32 v87, v173
	v_cvt_f32_ubyte2_e32 v86, v173
	v_pk_mul_f32 v[180:181], v[180:181], s[36:37] op_sel_hi:[1,0]
	v_pk_mul_f32 v[188:189], v[188:189], s[36:37] op_sel_hi:[1,0]
	v_pk_mul_f32 v[194:195], v[194:195], s[36:37] op_sel_hi:[1,0]
	v_pk_mul_f32 v[86:87], v[86:87], s[36:37] op_sel_hi:[1,0]
	v_pk_mul_f32 v[158:159], v[106:107], v[158:159]
	v_pk_mul_f32 v[106:107], v[130:131], v[180:181]
	v_pk_mul_f32 v[130:131], v[104:105], v[188:189]
	v_pk_mul_f32 v[104:105], v[124:125], v[194:195]
	v_pk_mul_f32 v[124:125], v[88:89], v[86:87]
	v_cvt_f32_ubyte1_e32 v89, v171
	v_cvt_f32_ubyte0_e32 v88, v171
	v_pk_mul_f32 v[88:89], v[88:89], s[36:37] op_sel_hi:[1,0]
	v_pk_mul_f32 v[184:185], v[184:185], s[36:37] op_sel_hi:[1,0]
	v_pk_mul_f32 v[88:89], v[94:95], v[88:89]
	v_cvt_f32_ubyte1_e32 v95, v168
	v_cvt_f32_ubyte0_e32 v94, v168
	v_pk_mul_f32 v[94:95], v[94:95], s[36:37] op_sel_hi:[1,0]
	v_pk_mul_f32 v[114:115], v[132:133], v[184:185]
	v_mad_i64_i32 v[132:133], s[0:1], v3, s88, v[164:165]
	v_cvt_f32_ubyte3_e32 v93, v171
	v_cvt_f32_ubyte2_e32 v92, v171
	v_pk_mul_f32 v[94:95], v[74:75], v[94:95]
	v_cvt_f32_ubyte1_e32 v75, v169
	v_cvt_f32_ubyte0_e32 v74, v169
	global_load_dwordx2 v[174:175], v[132:133], off nt
	v_cvt_f32_ubyte1_e32 v87, v170
	v_cvt_f32_ubyte0_e32 v86, v170
	v_pk_mul_f32 v[92:93], v[92:93], s[36:37] op_sel_hi:[1,0]
	v_pk_mul_f32 v[74:75], v[74:75], s[36:37] op_sel_hi:[1,0]
	v_pk_mul_f32 v[86:87], v[86:87], s[36:37] op_sel_hi:[1,0]
	v_add_u32_e32 v3, 0x90, v154
	v_pk_mul_f32 v[92:93], v[96:97], v[92:93]
	v_pk_mul_f32 v[96:97], v[70:71], v[74:75]
	v_cvt_f32_ubyte3_e32 v71, v168
	v_cvt_f32_ubyte2_e32 v70, v168
	v_pk_mul_f32 v[86:87], v[98:99], v[86:87]
	v_mad_i64_i32 v[98:99], s[0:1], v3, s88, v[164:165]
	v_pk_mul_f32 v[70:71], v[70:71], s[36:37] op_sel_hi:[1,0]
	v_cvt_f32_ubyte3_e32 v91, v170
	v_cvt_f32_ubyte2_e32 v90, v170
	global_load_dwordx2 v[172:173], v[98:99], off nt
	global_load_dwordx2 v[170:171], v[98:99], off offset:128 nt
	v_pk_mul_f32 v[98:99], v[76:77], v[70:71]
	v_cvt_f32_ubyte3_e32 v71, v169
	v_cvt_f32_ubyte2_e32 v70, v169
	v_pk_mul_f32 v[90:91], v[90:91], s[36:37] op_sel_hi:[1,0]
	v_pk_mul_f32 v[70:71], v[70:71], s[36:37] op_sel_hi:[1,0]
	v_pk_mul_f32 v[90:91], v[100:101], v[90:91]
	v_pk_mul_f32 v[100:101], v[72:73], v[70:71]
	v_cvt_f32_ubyte1_e32 v71, v166
	v_cvt_f32_ubyte0_e32 v70, v166
	v_pk_mul_f32 v[70:71], v[70:71], s[36:37] op_sel_hi:[1,0]
	v_add_u32_e32 v3, 0xa0, v154
	v_pk_mul_f32 v[70:71], v[82:83], v[70:71]
	v_mad_i64_i32 v[82:83], s[0:1], v3, s88, v[164:165]
	global_load_dwordx2 v[168:169], v[82:83], off nt
	v_cvt_f32_ubyte1_e32 v73, v167
	global_load_dwordx2 v[132:133], v[132:133], off offset:128 nt
	v_cvt_f32_ubyte0_e32 v72, v167
	v_cvt_f32_ubyte3_e32 v75, v166
	v_cvt_f32_ubyte2_e32 v74, v166
	v_pk_mul_f32 v[72:73], v[72:73], s[36:37] op_sel_hi:[1,0]
	v_pk_mul_f32 v[74:75], v[74:75], s[36:37] op_sel_hi:[1,0]
	v_add_u32_e32 v3, 0xb0, v154
	v_pk_mul_f32 v[72:73], v[78:79], v[72:73]
	v_pk_mul_f32 v[74:75], v[84:85], v[74:75]
	v_mad_i64_i32 v[78:79], s[0:1], v3, s88, v[164:165]
	global_load_dwordx2 v[82:83], v[82:83], off offset:128 nt
	s_nop 0
	global_load_dwordx2 v[84:85], v[78:79], off nt
	global_load_dwordx2 v[154:155], v[78:79], off offset:128 nt
	v_cvt_f32_ubyte3_e32 v77, v167
	v_cvt_f32_ubyte2_e32 v76, v167
	v_pk_mul_f32 v[76:77], v[76:77], s[36:37] op_sel_hi:[1,0]
	s_lshl_b32 s0, s71, 3
	v_pk_mul_f32 v[76:77], v[80:81], v[76:77]
	s_add_i32 s0, s0, s65
	s_ashr_i32 s1, s0, 31
	v_pk_mul_f32 v[190:191], v[190:191], s[36:37] op_sel_hi:[1,0]
	s_lshl_b64 s[0:1], s[0:1], 14
	v_pk_mul_f32 v[112:113], v[112:113], v[190:191]
	s_waitcnt vmcnt(7)
	v_cvt_f32_ubyte1_e32 v79, v174
	v_cvt_f32_ubyte0_e32 v78, v174
	v_pk_mul_f32 v[78:79], v[78:79], s[36:37] op_sel_hi:[1,0]
	s_nop 0
	v_pk_mul_f32 v[66:67], v[66:67], v[78:79]
	v_cvt_f32_ubyte1_e32 v79, v175
	v_cvt_f32_ubyte0_e32 v78, v175
	v_pk_mul_f32 v[78:79], v[78:79], s[36:37] op_sel_hi:[1,0]
	s_nop 0
	v_pk_mul_f32 v[78:79], v[58:59], v[78:79]
	v_cvt_f32_ubyte3_e32 v59, v174
	v_cvt_f32_ubyte2_e32 v58, v174
	v_pk_mul_f32 v[58:59], v[58:59], s[36:37] op_sel_hi:[1,0]
	s_nop 0
	v_pk_mul_f32 v[68:69], v[68:69], v[58:59]
	v_cvt_f32_ubyte3_e32 v59, v175
	v_cvt_f32_ubyte2_e32 v58, v175
	v_pk_mul_f32 v[58:59], v[58:59], s[36:37] op_sel_hi:[1,0]
	s_nop 0
	v_pk_mul_f32 v[80:81], v[60:61], v[58:59]
	s_waitcnt vmcnt(3)
	v_cvt_f32_ubyte1_e32 v59, v132
	v_cvt_f32_ubyte0_e32 v58, v132
	v_pk_mul_f32 v[58:59], v[58:59], s[36:37] op_sel_hi:[1,0]
	v_cvt_f32_ubyte1_e32 v61, v133
	v_pk_mul_f32 v[58:59], v[62:63], v[58:59]
	v_cvt_f32_ubyte3_e32 v63, v133
	v_cvt_f32_ubyte2_e32 v62, v133
	v_pk_mul_f32 v[62:63], v[62:63], s[36:37] op_sel_hi:[1,0]
	v_cvt_f32_ubyte0_e32 v60, v133
	v_pk_mul_f32 v[56:57], v[56:57], v[62:63]
	v_cvt_f32_ubyte1_e32 v63, v172
	v_cvt_f32_ubyte0_e32 v62, v172
	v_pk_mul_f32 v[62:63], v[62:63], s[36:37] op_sel_hi:[1,0]
	v_pk_mul_f32 v[60:61], v[60:61], s[36:37] op_sel_hi:[1,0]
	v_pk_mul_f32 v[50:51], v[50:51], v[62:63]
	v_cvt_f32_ubyte1_e32 v63, v173
	v_cvt_f32_ubyte0_e32 v62, v173
	v_pk_mul_f32 v[62:63], v[62:63], s[36:37] op_sel_hi:[1,0]
	v_pk_mul_f32 v[54:55], v[54:55], v[60:61]
	v_pk_mul_f32 v[62:63], v[42:43], v[62:63]
	v_cvt_f32_ubyte3_e32 v43, v172
	v_cvt_f32_ubyte2_e32 v42, v172
	v_pk_mul_f32 v[42:43], v[42:43], s[36:37] op_sel_hi:[1,0]
	v_cvt_f32_ubyte3_e32 v61, v132
	v_cvt_f32_ubyte2_e32 v60, v132
	v_pk_mul_f32 v[52:53], v[52:53], v[42:43]
	v_cvt_f32_ubyte3_e32 v43, v173
	v_cvt_f32_ubyte2_e32 v42, v173
	v_pk_mul_f32 v[60:61], v[60:61], s[36:37] op_sel_hi:[1,0]
	v_pk_mul_f32 v[42:43], v[42:43], s[36:37] op_sel_hi:[1,0]
	v_pk_mul_f32 v[60:61], v[64:65], v[60:61]
	v_pk_mul_f32 v[64:65], v[44:45], v[42:43]
	v_cvt_f32_ubyte1_e32 v43, v170
	v_cvt_f32_ubyte0_e32 v42, v170
	v_pk_mul_f32 v[42:43], v[42:43], s[36:37] op_sel_hi:[1,0]
	v_cvt_f32_ubyte1_e32 v45, v171
	v_pk_mul_f32 v[42:43], v[46:47], v[42:43]
	v_cvt_f32_ubyte3_e32 v47, v171
	v_cvt_f32_ubyte2_e32 v46, v171
	v_pk_mul_f32 v[46:47], v[46:47], s[36:37] op_sel_hi:[1,0]
	v_cvt_f32_ubyte0_e32 v44, v171
	v_pk_mul_f32 v[40:41], v[40:41], v[46:47]
	v_cvt_f32_ubyte1_e32 v47, v168
	v_cvt_f32_ubyte0_e32 v46, v168
	v_pk_mul_f32 v[46:47], v[46:47], s[36:37] op_sel_hi:[1,0]
	v_pk_mul_f32 v[44:45], v[44:45], s[36:37] op_sel_hi:[1,0]
	v_pk_mul_f32 v[34:35], v[34:35], v[46:47]
	v_cvt_f32_ubyte1_e32 v47, v169
	v_cvt_f32_ubyte0_e32 v46, v169
	v_pk_mul_f32 v[46:47], v[46:47], s[36:37] op_sel_hi:[1,0]
	v_pk_mul_f32 v[38:39], v[38:39], v[44:45]
	v_pk_mul_f32 v[26:27], v[26:27], v[46:47]
	v_cvt_f32_ubyte3_e32 v47, v168
	v_cvt_f32_ubyte2_e32 v46, v168
	v_pk_mul_f32 v[46:47], v[46:47], s[36:37] op_sel_hi:[1,0]
	v_cvt_f32_ubyte3_e32 v45, v170
	v_pk_mul_f32 v[36:37], v[36:37], v[46:47]
	v_cvt_f32_ubyte3_e32 v47, v169
	v_cvt_f32_ubyte2_e32 v46, v169
	v_pk_mul_f32 v[46:47], v[46:47], s[36:37] op_sel_hi:[1,0]
	v_cvt_f32_ubyte2_e32 v44, v170
	v_pk_mul_f32 v[28:29], v[28:29], v[46:47]
	s_waitcnt vmcnt(2)
	v_cvt_f32_ubyte1_e32 v47, v82
	v_cvt_f32_ubyte0_e32 v46, v82
	v_pk_mul_f32 v[46:47], v[46:47], s[36:37] op_sel_hi:[1,0]
	v_pk_mul_f32 v[44:45], v[44:45], s[36:37] op_sel_hi:[1,0]
	v_pk_mul_f32 v[30:31], v[30:31], v[46:47]
	v_cvt_f32_ubyte1_e32 v47, v83
	v_cvt_f32_ubyte0_e32 v46, v83
	v_pk_mul_f32 v[46:47], v[46:47], s[36:37] op_sel_hi:[1,0]
	v_pk_mul_f32 v[44:45], v[48:49], v[44:45]
	v_pk_mul_f32 v[22:23], v[22:23], v[46:47]
	v_cvt_f32_ubyte3_e32 v47, v82
	v_cvt_f32_ubyte2_e32 v46, v82
	v_pk_mul_f32 v[46:47], v[46:47], s[36:37] op_sel_hi:[1,0]
	s_nop 0
	v_pk_mul_f32 v[32:33], v[32:33], v[46:47]
	v_cvt_f32_ubyte3_e32 v47, v83
	v_cvt_f32_ubyte2_e32 v46, v83
	v_pk_mul_f32 v[46:47], v[46:47], s[36:37] op_sel_hi:[1,0]
	v_lshl_add_u64 v[82:83], v[146:147], 0, s[0:1]
	v_pk_mul_f32 v[24:25], v[24:25], v[46:47]
	s_waitcnt vmcnt(1)
	v_cvt_f32_ubyte1_e32 v47, v84
	v_cvt_f32_ubyte0_e32 v46, v84
	v_pk_mul_f32 v[46:47], v[46:47], s[36:37] op_sel_hi:[1,0]
	s_nop 0
	v_pk_mul_f32 v[18:19], v[18:19], v[46:47]
	v_cvt_f32_ubyte1_e32 v47, v85
	v_cvt_f32_ubyte0_e32 v46, v85
	v_pk_mul_f32 v[46:47], v[46:47], s[36:37] op_sel_hi:[1,0]
	s_nop 0
	v_pk_mul_f32 v[10:11], v[10:11], v[46:47]
	v_cvt_f32_ubyte3_e32 v47, v84
	v_cvt_f32_ubyte2_e32 v46, v84
	v_pk_mul_f32 v[46:47], v[46:47], s[36:37] op_sel_hi:[1,0]
	s_nop 0
	v_pk_mul_f32 v[20:21], v[20:21], v[46:47]
	v_cvt_f32_ubyte3_e32 v47, v85
	v_cvt_f32_ubyte2_e32 v46, v85
	v_pk_mul_f32 v[46:47], v[46:47], s[36:37] op_sel_hi:[1,0]
	s_nop 0
	v_pk_mul_f32 v[12:13], v[12:13], v[46:47]
	s_waitcnt vmcnt(0)
	v_cvt_f32_ubyte1_e32 v47, v154
	v_cvt_f32_ubyte0_e32 v46, v154
	v_pk_mul_f32 v[46:47], v[46:47], s[36:37] op_sel_hi:[1,0]
	s_nop 0
	v_pk_mul_f32 v[14:15], v[14:15], v[46:47]
	v_cvt_f32_ubyte1_e32 v47, v155
	v_cvt_f32_ubyte0_e32 v46, v155
	v_pk_mul_f32 v[46:47], v[46:47], s[36:37] op_sel_hi:[1,0]
	s_nop 0
	v_pk_mul_f32 v[46:47], v[6:7], v[46:47]
	v_cvt_f32_ubyte3_e32 v7, v154
	v_cvt_f32_ubyte2_e32 v6, v154
	v_pk_mul_f32 v[6:7], v[6:7], s[36:37] op_sel_hi:[1,0]
	s_nop 0
	v_pk_mul_f32 v[16:17], v[16:17], v[6:7]
	v_cvt_f32_ubyte3_e32 v7, v155
	v_cvt_f32_ubyte2_e32 v6, v155
	v_pk_mul_f32 v[6:7], v[6:7], s[36:37] op_sel_hi:[1,0]
	s_nop 0
	v_pk_mul_f32 v[48:49], v[8:9], v[6:7]
	v_cvt_pk_bf16_f32 v6, v158, v159
	v_cvt_pk_bf16_f32 v7, v162, v163
	v_cvt_pk_bf16_f32 v8, v156, v157
	v_cvt_pk_bf16_f32 v9, v160, v161
	global_store_dwordx4 v[82:83], v[6:9], off
	s_nop 1
	v_cvt_pk_bf16_f32 v6, v128, v129
	v_cvt_pk_bf16_f32 v7, v130, v131
	v_cvt_pk_bf16_f32 v8, v126, v127
	v_cvt_pk_bf16_f32 v9, v112, v113
	global_store_dwordx4 v[82:83], v[6:9], off offset:1024
	s_nop 1
	v_cvt_pk_bf16_f32 v6, v118, v119
	v_cvt_pk_bf16_f32 v7, v122, v123
	v_cvt_pk_bf16_f32 v8, v120, v121
	v_cvt_pk_bf16_f32 v9, v124, v125
	global_store_dwordx4 v[82:83], v[6:9], off offset:2048
	s_nop 1
	v_cvt_pk_bf16_f32 v6, v94, v95
	v_cvt_pk_bf16_f32 v7, v98, v99
	v_cvt_pk_bf16_f32 v8, v96, v97
	v_cvt_pk_bf16_f32 v9, v100, v101
	global_store_dwordx4 v[82:83], v[6:9], off offset:3072
	v_lshl_add_u64 v[82:83], v[82:83], 0, s[40:41]
	s_nop 0
	v_cvt_pk_bf16_f32 v6, v108, v109
	v_cvt_pk_bf16_f32 v7, v116, v117
	v_cvt_pk_bf16_f32 v8, v106, v107
	v_cvt_pk_bf16_f32 v9, v114, v115
	flat_store_dwordx4 v[82:83], v[6:9]
	s_nop 1
	v_cvt_pk_bf16_f32 v6, v102, v103
	v_cvt_pk_bf16_f32 v7, v104, v105
	v_cvt_pk_bf16_f32 v8, v4, v5
	v_cvt_pk_bf16_f32 v9, v110, v111
	flat_store_dwordx4 v[82:83], v[6:9] offset:1024
	v_cvt_pk_bf16_f32 v4, v86, v87
	v_cvt_pk_bf16_f32 v5, v90, v91
	v_cvt_pk_bf16_f32 v6, v88, v89
	v_cvt_pk_bf16_f32 v7, v92, v93
	flat_store_dwordx4 v[82:83], v[4:7] offset:2048
	v_lshl_add_u64 v[8:9], v[82:83], 0, s[40:41]
	s_nop 0
	v_cvt_pk_bf16_f32 v4, v70, v71
	v_cvt_pk_bf16_f32 v5, v74, v75
	v_cvt_pk_bf16_f32 v6, v72, v73
	v_cvt_pk_bf16_f32 v7, v76, v77
	flat_store_dwordx4 v[82:83], v[4:7] offset:3072
	s_nop 1
	v_cvt_pk_bf16_f32 v4, v66, v67
	v_cvt_pk_bf16_f32 v5, v68, v69
	v_cvt_pk_bf16_f32 v6, v78, v79
	v_cvt_pk_bf16_f32 v7, v80, v81
	flat_store_dwordx4 v[8:9], v[4:7]
	s_nop 1
	v_cvt_pk_bf16_f32 v4, v50, v51
	v_cvt_pk_bf16_f32 v5, v52, v53
	v_cvt_pk_bf16_f32 v6, v62, v63
	v_cvt_pk_bf16_f32 v7, v64, v65
	flat_store_dwordx4 v[8:9], v[4:7] offset:1024
	s_nop 1
	v_cvt_pk_bf16_f32 v4, v34, v35
	v_cvt_pk_bf16_f32 v5, v36, v37
	v_cvt_pk_bf16_f32 v6, v26, v27
	v_cvt_pk_bf16_f32 v7, v28, v29
	flat_store_dwordx4 v[8:9], v[4:7] offset:2048
	s_nop 1
	v_cvt_pk_bf16_f32 v4, v18, v19
	v_cvt_pk_bf16_f32 v5, v20, v21
	v_cvt_pk_bf16_f32 v6, v10, v11
	v_cvt_pk_bf16_f32 v7, v12, v13
	flat_store_dwordx4 v[8:9], v[4:7] offset:3072
	v_lshl_add_u64 v[8:9], v[8:9], 0, s[40:41]
	s_nop 0
	v_cvt_pk_bf16_f32 v4, v58, v59
	v_cvt_pk_bf16_f32 v5, v60, v61
	v_cvt_pk_bf16_f32 v6, v54, v55
	v_cvt_pk_bf16_f32 v7, v56, v57
	flat_store_dwordx4 v[8:9], v[4:7]
	s_nop 1
	v_cvt_pk_bf16_f32 v4, v42, v43
	v_cvt_pk_bf16_f32 v5, v44, v45
	v_cvt_pk_bf16_f32 v6, v38, v39
	v_cvt_pk_bf16_f32 v7, v40, v41
	flat_store_dwordx4 v[8:9], v[4:7] offset:1024
	s_nop 1
	v_cvt_pk_bf16_f32 v4, v30, v31
	v_cvt_pk_bf16_f32 v5, v32, v33
	v_cvt_pk_bf16_f32 v6, v22, v23
	v_cvt_pk_bf16_f32 v7, v24, v25
	flat_store_dwordx4 v[8:9], v[4:7] offset:2048
	s_nop 1
	v_cvt_pk_bf16_f32 v4, v14, v15
	v_cvt_pk_bf16_f32 v5, v16, v17
	v_cvt_pk_bf16_f32 v6, v46, v47
	v_cvt_pk_bf16_f32 v7, v48, v49
	flat_store_dwordx4 v[8:9], v[4:7] offset:3072
	s_nop 1
	v_lshl_add_u64 v[4:5], v[8:9], 0, s[40:41]
